# gather group loop: 16 down-row loads issued before the 16 up-row loads, vmcnt waits recounted (down 30..16, up 15..0)
# speedup vs baseline: 1.0030x; 1.0030x over previous
.LBB0_1062:
	s_or_b64 exec, exec, s[22:23]
	s_waitcnt lgkmcnt(0)
	v_mul_f32_e32 v78, 0.5, v78
	v_mul_f32_e32 v78, v78, v79
	v_bfi_b32 v79, s34, v81, v80
	v_add_f32_e32 v79, 1.0, v79
	v_mul_f32_e32 v89, v78, v79
	s_waitcnt vmcnt(15)
	v_cvt_scalef32_pk_f32_fp4 v[78:79], v74, 1.0
	v_readlane_b32 s22, v89, 0
	v_cvt_scalef32_pk_f32_fp4 v[80:81], v74, 1.0 op_sel:[1,0,0]
	v_cvt_scalef32_pk_f32_fp4 v[90:91], v74, 1.0 op_sel:[0,1,0]
	v_cvt_scalef32_pk_f32_fp4 v[92:93], v74, 1.0 op_sel:[1,1,0]
	v_cvt_scalef32_pk_f32_fp4 v[94:95], v75, 1.0
	v_cvt_scalef32_pk_f32_fp4 v[96:97], v75, 1.0 op_sel:[1,0,0]
	v_cvt_scalef32_pk_f32_fp4 v[98:99], v75, 1.0 op_sel:[0,1,0]
	v_cvt_scalef32_pk_f32_fp4 v[74:75], v75, 1.0 op_sel:[1,1,0]
	v_pk_fma_f32 v[38:39], v[78:79], s[22:23], v[38:39] op_sel_hi:[1,0,1]
	v_pk_fma_f32 v[40:41], s[22:23], v[80:81], v[40:41] op_sel_hi:[0,1,1]
	v_pk_fma_f32 v[34:35], s[22:23], v[90:91], v[34:35] op_sel_hi:[0,1,1]
	v_pk_fma_f32 v[36:37], s[22:23], v[92:93], v[36:37] op_sel_hi:[0,1,1]
	v_pk_fma_f32 v[28:29], s[22:23], v[94:95], v[28:29] op_sel_hi:[0,1,1]
	v_pk_fma_f32 v[30:31], s[22:23], v[96:97], v[30:31] op_sel_hi:[0,1,1]
	v_pk_fma_f32 v[26:27], s[22:23], v[98:99], v[26:27] op_sel_hi:[0,1,1]
	v_pk_fma_f32 v[32:33], s[22:23], v[74:75], v[32:33] op_sel_hi:[0,1,1]
	v_readlane_b32 s22, v89, 1
	s_waitcnt vmcnt(14)
	v_cvt_scalef32_pk_f32_fp4 v[74:75], v70, 1.0
	v_cvt_scalef32_pk_f32_fp4 v[78:79], v70, 1.0 op_sel:[1,0,0]
	v_cvt_scalef32_pk_f32_fp4 v[80:81], v70, 1.0 op_sel:[0,1,0]
	v_cvt_scalef32_pk_f32_fp4 v[90:91], v70, 1.0 op_sel:[1,1,0]
	v_cvt_scalef32_pk_f32_fp4 v[92:93], v71, 1.0
	v_cvt_scalef32_pk_f32_fp4 v[94:95], v71, 1.0 op_sel:[1,0,0]
	v_cvt_scalef32_pk_f32_fp4 v[96:97], v71, 1.0 op_sel:[0,1,0]
	v_cvt_scalef32_pk_f32_fp4 v[70:71], v71, 1.0 op_sel:[1,1,0]
	v_pk_fma_f32 v[38:39], v[74:75], s[22:23], v[38:39] op_sel_hi:[1,0,1]
	v_pk_fma_f32 v[40:41], s[22:23], v[78:79], v[40:41] op_sel_hi:[0,1,1]
	v_pk_fma_f32 v[34:35], s[22:23], v[80:81], v[34:35] op_sel_hi:[0,1,1]
	v_pk_fma_f32 v[36:37], s[22:23], v[90:91], v[36:37] op_sel_hi:[0,1,1]
	v_pk_fma_f32 v[28:29], s[22:23], v[92:93], v[28:29] op_sel_hi:[0,1,1]
	v_pk_fma_f32 v[30:31], s[22:23], v[94:95], v[30:31] op_sel_hi:[0,1,1]
	v_pk_fma_f32 v[26:27], s[22:23], v[96:97], v[26:27] op_sel_hi:[0,1,1]
	v_pk_fma_f32 v[32:33], s[22:23], v[70:71], v[32:33] op_sel_hi:[0,1,1]
	v_readlane_b32 s22, v89, 2
	s_waitcnt vmcnt(13)
	v_cvt_scalef32_pk_f32_fp4 v[70:71], v68, 1.0
	v_cvt_scalef32_pk_f32_fp4 v[74:75], v68, 1.0 op_sel:[1,0,0]
	v_cvt_scalef32_pk_f32_fp4 v[78:79], v68, 1.0 op_sel:[0,1,0]
	v_cvt_scalef32_pk_f32_fp4 v[80:81], v68, 1.0 op_sel:[1,1,0]
	v_cvt_scalef32_pk_f32_fp4 v[90:91], v69, 1.0
	v_cvt_scalef32_pk_f32_fp4 v[92:93], v69, 1.0 op_sel:[1,0,0]
	v_cvt_scalef32_pk_f32_fp4 v[94:95], v69, 1.0 op_sel:[0,1,0]
	v_cvt_scalef32_pk_f32_fp4 v[68:69], v69, 1.0 op_sel:[1,1,0]
	v_pk_fma_f32 v[38:39], v[70:71], s[22:23], v[38:39] op_sel_hi:[1,0,1]
	v_pk_fma_f32 v[40:41], s[22:23], v[74:75], v[40:41] op_sel_hi:[0,1,1]
	v_pk_fma_f32 v[34:35], s[22:23], v[78:79], v[34:35] op_sel_hi:[0,1,1]
	v_pk_fma_f32 v[36:37], s[22:23], v[80:81], v[36:37] op_sel_hi:[0,1,1]
	v_pk_fma_f32 v[28:29], s[22:23], v[90:91], v[28:29] op_sel_hi:[0,1,1]
	v_pk_fma_f32 v[30:31], s[22:23], v[92:93], v[30:31] op_sel_hi:[0,1,1]
	v_pk_fma_f32 v[26:27], s[22:23], v[94:95], v[26:27] op_sel_hi:[0,1,1]
	v_pk_fma_f32 v[32:33], s[22:23], v[68:69], v[32:33] op_sel_hi:[0,1,1]
	v_readlane_b32 s22, v89, 3
	s_waitcnt vmcnt(12)
	v_cvt_scalef32_pk_f32_fp4 v[68:69], v66, 1.0
	v_cvt_scalef32_pk_f32_fp4 v[70:71], v66, 1.0 op_sel:[1,0,0]
	v_cvt_scalef32_pk_f32_fp4 v[74:75], v66, 1.0 op_sel:[0,1,0]
	v_cvt_scalef32_pk_f32_fp4 v[78:79], v66, 1.0 op_sel:[1,1,0]
	v_cvt_scalef32_pk_f32_fp4 v[80:81], v67, 1.0
	v_cvt_scalef32_pk_f32_fp4 v[90:91], v67, 1.0 op_sel:[1,0,0]
	v_cvt_scalef32_pk_f32_fp4 v[92:93], v67, 1.0 op_sel:[0,1,0]
	v_cvt_scalef32_pk_f32_fp4 v[66:67], v67, 1.0 op_sel:[1,1,0]
	v_pk_fma_f32 v[38:39], v[68:69], s[22:23], v[38:39] op_sel_hi:[1,0,1]
	v_pk_fma_f32 v[40:41], s[22:23], v[70:71], v[40:41] op_sel_hi:[0,1,1]
	v_pk_fma_f32 v[34:35], s[22:23], v[74:75], v[34:35] op_sel_hi:[0,1,1]
	v_pk_fma_f32 v[36:37], s[22:23], v[78:79], v[36:37] op_sel_hi:[0,1,1]
	v_pk_fma_f32 v[28:29], s[22:23], v[80:81], v[28:29] op_sel_hi:[0,1,1]
	v_pk_fma_f32 v[30:31], s[22:23], v[90:91], v[30:31] op_sel_hi:[0,1,1]
	v_pk_fma_f32 v[26:27], s[22:23], v[92:93], v[26:27] op_sel_hi:[0,1,1]
	v_pk_fma_f32 v[32:33], s[22:23], v[66:67], v[32:33] op_sel_hi:[0,1,1]
	v_readlane_b32 s22, v89, 4
	s_waitcnt vmcnt(11)
	v_cvt_scalef32_pk_f32_fp4 v[66:67], v64, 1.0
	v_cvt_scalef32_pk_f32_fp4 v[68:69], v64, 1.0 op_sel:[1,0,0]
	v_cvt_scalef32_pk_f32_fp4 v[70:71], v64, 1.0 op_sel:[0,1,0]
	v_cvt_scalef32_pk_f32_fp4 v[74:75], v64, 1.0 op_sel:[1,1,0]
	v_cvt_scalef32_pk_f32_fp4 v[78:79], v65, 1.0
	v_cvt_scalef32_pk_f32_fp4 v[80:81], v65, 1.0 op_sel:[1,0,0]
	v_cvt_scalef32_pk_f32_fp4 v[90:91], v65, 1.0 op_sel:[0,1,0]
	v_cvt_scalef32_pk_f32_fp4 v[64:65], v65, 1.0 op_sel:[1,1,0]
	v_pk_fma_f32 v[38:39], v[66:67], s[22:23], v[38:39] op_sel_hi:[1,0,1]
	v_pk_fma_f32 v[40:41], s[22:23], v[68:69], v[40:41] op_sel_hi:[0,1,1]
	v_pk_fma_f32 v[34:35], s[22:23], v[70:71], v[34:35] op_sel_hi:[0,1,1]
	v_pk_fma_f32 v[36:37], s[22:23], v[74:75], v[36:37] op_sel_hi:[0,1,1]
	v_pk_fma_f32 v[28:29], s[22:23], v[78:79], v[28:29] op_sel_hi:[0,1,1]
	v_pk_fma_f32 v[30:31], s[22:23], v[80:81], v[30:31] op_sel_hi:[0,1,1]
	v_pk_fma_f32 v[26:27], s[22:23], v[90:91], v[26:27] op_sel_hi:[0,1,1]
	v_pk_fma_f32 v[32:33], s[22:23], v[64:65], v[32:33] op_sel_hi:[0,1,1]
	v_readlane_b32 s22, v89, 5
	s_waitcnt vmcnt(10)
	v_cvt_scalef32_pk_f32_fp4 v[64:65], v62, 1.0
	v_cvt_scalef32_pk_f32_fp4 v[66:67], v62, 1.0 op_sel:[1,0,0]
	v_cvt_scalef32_pk_f32_fp4 v[68:69], v62, 1.0 op_sel:[0,1,0]
	v_cvt_scalef32_pk_f32_fp4 v[70:71], v62, 1.0 op_sel:[1,1,0]
	v_cvt_scalef32_pk_f32_fp4 v[74:75], v63, 1.0
	v_cvt_scalef32_pk_f32_fp4 v[78:79], v63, 1.0 op_sel:[1,0,0]
	v_cvt_scalef32_pk_f32_fp4 v[80:81], v63, 1.0 op_sel:[0,1,0]
	v_cvt_scalef32_pk_f32_fp4 v[62:63], v63, 1.0 op_sel:[1,1,0]
	v_pk_fma_f32 v[38:39], v[64:65], s[22:23], v[38:39] op_sel_hi:[1,0,1]
	v_pk_fma_f32 v[40:41], s[22:23], v[66:67], v[40:41] op_sel_hi:[0,1,1]
	v_pk_fma_f32 v[34:35], s[22:23], v[68:69], v[34:35] op_sel_hi:[0,1,1]
	v_pk_fma_f32 v[36:37], s[22:23], v[70:71], v[36:37] op_sel_hi:[0,1,1]
	v_pk_fma_f32 v[28:29], s[22:23], v[74:75], v[28:29] op_sel_hi:[0,1,1]
	v_pk_fma_f32 v[30:31], s[22:23], v[78:79], v[30:31] op_sel_hi:[0,1,1]
	v_pk_fma_f32 v[26:27], s[22:23], v[80:81], v[26:27] op_sel_hi:[0,1,1]
	v_pk_fma_f32 v[32:33], s[22:23], v[62:63], v[32:33] op_sel_hi:[0,1,1]
	v_readlane_b32 s22, v89, 6
	s_waitcnt vmcnt(9)
	v_cvt_scalef32_pk_f32_fp4 v[62:63], v60, 1.0
	v_cvt_scalef32_pk_f32_fp4 v[64:65], v60, 1.0 op_sel:[1,0,0]
	v_cvt_scalef32_pk_f32_fp4 v[66:67], v60, 1.0 op_sel:[0,1,0]
	v_cvt_scalef32_pk_f32_fp4 v[68:69], v60, 1.0 op_sel:[1,1,0]
	v_cvt_scalef32_pk_f32_fp4 v[70:71], v61, 1.0
	v_cvt_scalef32_pk_f32_fp4 v[74:75], v61, 1.0 op_sel:[1,0,0]
	v_cvt_scalef32_pk_f32_fp4 v[78:79], v61, 1.0 op_sel:[0,1,0]
	v_cvt_scalef32_pk_f32_fp4 v[60:61], v61, 1.0 op_sel:[1,1,0]
	v_pk_fma_f32 v[38:39], v[62:63], s[22:23], v[38:39] op_sel_hi:[1,0,1]
	v_pk_fma_f32 v[40:41], s[22:23], v[64:65], v[40:41] op_sel_hi:[0,1,1]
	v_pk_fma_f32 v[34:35], s[22:23], v[66:67], v[34:35] op_sel_hi:[0,1,1]
	v_pk_fma_f32 v[36:37], s[22:23], v[68:69], v[36:37] op_sel_hi:[0,1,1]
	v_pk_fma_f32 v[28:29], s[22:23], v[70:71], v[28:29] op_sel_hi:[0,1,1]
	v_pk_fma_f32 v[30:31], s[22:23], v[74:75], v[30:31] op_sel_hi:[0,1,1]
	v_pk_fma_f32 v[26:27], s[22:23], v[78:79], v[26:27] op_sel_hi:[0,1,1]
	v_pk_fma_f32 v[32:33], s[22:23], v[60:61], v[32:33] op_sel_hi:[0,1,1]
	v_readlane_b32 s22, v89, 7
	s_waitcnt vmcnt(8)
	v_cvt_scalef32_pk_f32_fp4 v[60:61], v58, 1.0
	v_cvt_scalef32_pk_f32_fp4 v[62:63], v58, 1.0 op_sel:[1,0,0]
	v_cvt_scalef32_pk_f32_fp4 v[64:65], v58, 1.0 op_sel:[0,1,0]
	v_cvt_scalef32_pk_f32_fp4 v[66:67], v58, 1.0 op_sel:[1,1,0]
	v_cvt_scalef32_pk_f32_fp4 v[68:69], v59, 1.0
	v_cvt_scalef32_pk_f32_fp4 v[70:71], v59, 1.0 op_sel:[1,0,0]
	v_cvt_scalef32_pk_f32_fp4 v[74:75], v59, 1.0 op_sel:[0,1,0]
	v_cvt_scalef32_pk_f32_fp4 v[58:59], v59, 1.0 op_sel:[1,1,0]
	v_pk_fma_f32 v[38:39], v[60:61], s[22:23], v[38:39] op_sel_hi:[1,0,1]
	v_pk_fma_f32 v[40:41], s[22:23], v[62:63], v[40:41] op_sel_hi:[0,1,1]
	v_pk_fma_f32 v[34:35], s[22:23], v[64:65], v[34:35] op_sel_hi:[0,1,1]
	v_pk_fma_f32 v[36:37], s[22:23], v[66:67], v[36:37] op_sel_hi:[0,1,1]
	v_pk_fma_f32 v[28:29], s[22:23], v[68:69], v[28:29] op_sel_hi:[0,1,1]
	v_pk_fma_f32 v[30:31], s[22:23], v[70:71], v[30:31] op_sel_hi:[0,1,1]
	v_pk_fma_f32 v[26:27], s[22:23], v[74:75], v[26:27] op_sel_hi:[0,1,1]
	v_pk_fma_f32 v[32:33], s[22:23], v[58:59], v[32:33] op_sel_hi:[0,1,1]
	v_readlane_b32 s22, v89, 8
	s_waitcnt vmcnt(7)
	v_cvt_scalef32_pk_f32_fp4 v[58:59], v56, 1.0
	v_cvt_scalef32_pk_f32_fp4 v[60:61], v56, 1.0 op_sel:[1,0,0]
	v_cvt_scalef32_pk_f32_fp4 v[62:63], v56, 1.0 op_sel:[0,1,0]
	v_cvt_scalef32_pk_f32_fp4 v[64:65], v56, 1.0 op_sel:[1,1,0]
	v_cvt_scalef32_pk_f32_fp4 v[66:67], v57, 1.0
	v_cvt_scalef32_pk_f32_fp4 v[68:69], v57, 1.0 op_sel:[1,0,0]
	v_cvt_scalef32_pk_f32_fp4 v[70:71], v57, 1.0 op_sel:[0,1,0]
	v_cvt_scalef32_pk_f32_fp4 v[56:57], v57, 1.0 op_sel:[1,1,0]
	v_pk_fma_f32 v[38:39], v[58:59], s[22:23], v[38:39] op_sel_hi:[1,0,1]
	v_pk_fma_f32 v[40:41], s[22:23], v[60:61], v[40:41] op_sel_hi:[0,1,1]
	v_pk_fma_f32 v[34:35], s[22:23], v[62:63], v[34:35] op_sel_hi:[0,1,1]
	v_pk_fma_f32 v[36:37], s[22:23], v[64:65], v[36:37] op_sel_hi:[0,1,1]
	v_pk_fma_f32 v[28:29], s[22:23], v[66:67], v[28:29] op_sel_hi:[0,1,1]
	v_pk_fma_f32 v[30:31], s[22:23], v[68:69], v[30:31] op_sel_hi:[0,1,1]
	v_pk_fma_f32 v[26:27], s[22:23], v[70:71], v[26:27] op_sel_hi:[0,1,1]
	v_pk_fma_f32 v[32:33], s[22:23], v[56:57], v[32:33] op_sel_hi:[0,1,1]
	v_readlane_b32 s22, v89, 9
	s_waitcnt vmcnt(6)
	v_cvt_scalef32_pk_f32_fp4 v[56:57], v54, 1.0
	v_cvt_scalef32_pk_f32_fp4 v[58:59], v54, 1.0 op_sel:[1,0,0]
	v_cvt_scalef32_pk_f32_fp4 v[60:61], v54, 1.0 op_sel:[0,1,0]
	v_cvt_scalef32_pk_f32_fp4 v[62:63], v54, 1.0 op_sel:[1,1,0]
	v_cvt_scalef32_pk_f32_fp4 v[64:65], v55, 1.0
	v_cvt_scalef32_pk_f32_fp4 v[66:67], v55, 1.0 op_sel:[1,0,0]
	v_cvt_scalef32_pk_f32_fp4 v[68:69], v55, 1.0 op_sel:[0,1,0]
	v_cvt_scalef32_pk_f32_fp4 v[54:55], v55, 1.0 op_sel:[1,1,0]
	v_pk_fma_f32 v[38:39], v[56:57], s[22:23], v[38:39] op_sel_hi:[1,0,1]
	v_pk_fma_f32 v[40:41], s[22:23], v[58:59], v[40:41] op_sel_hi:[0,1,1]
	v_pk_fma_f32 v[34:35], s[22:23], v[60:61], v[34:35] op_sel_hi:[0,1,1]
	v_pk_fma_f32 v[36:37], s[22:23], v[62:63], v[36:37] op_sel_hi:[0,1,1]
	v_pk_fma_f32 v[28:29], s[22:23], v[64:65], v[28:29] op_sel_hi:[0,1,1]
	v_pk_fma_f32 v[30:31], s[22:23], v[66:67], v[30:31] op_sel_hi:[0,1,1]
	v_pk_fma_f32 v[26:27], s[22:23], v[68:69], v[26:27] op_sel_hi:[0,1,1]
	v_pk_fma_f32 v[32:33], s[22:23], v[54:55], v[32:33] op_sel_hi:[0,1,1]
	v_readlane_b32 s22, v89, 10
	s_waitcnt vmcnt(5)
	v_cvt_scalef32_pk_f32_fp4 v[54:55], v52, 1.0
	v_cvt_scalef32_pk_f32_fp4 v[56:57], v52, 1.0 op_sel:[1,0,0]
	v_cvt_scalef32_pk_f32_fp4 v[58:59], v52, 1.0 op_sel:[0,1,0]
	v_cvt_scalef32_pk_f32_fp4 v[60:61], v52, 1.0 op_sel:[1,1,0]
	v_cvt_scalef32_pk_f32_fp4 v[62:63], v53, 1.0
	v_cvt_scalef32_pk_f32_fp4 v[64:65], v53, 1.0 op_sel:[1,0,0]
	v_cvt_scalef32_pk_f32_fp4 v[66:67], v53, 1.0 op_sel:[0,1,0]
	v_cvt_scalef32_pk_f32_fp4 v[52:53], v53, 1.0 op_sel:[1,1,0]
	v_pk_fma_f32 v[38:39], v[54:55], s[22:23], v[38:39] op_sel_hi:[1,0,1]
	v_pk_fma_f32 v[40:41], s[22:23], v[56:57], v[40:41] op_sel_hi:[0,1,1]
	v_pk_fma_f32 v[34:35], s[22:23], v[58:59], v[34:35] op_sel_hi:[0,1,1]
	v_pk_fma_f32 v[36:37], s[22:23], v[60:61], v[36:37] op_sel_hi:[0,1,1]
	v_pk_fma_f32 v[28:29], s[22:23], v[62:63], v[28:29] op_sel_hi:[0,1,1]
	v_pk_fma_f32 v[30:31], s[22:23], v[64:65], v[30:31] op_sel_hi:[0,1,1]
	v_pk_fma_f32 v[26:27], s[22:23], v[66:67], v[26:27] op_sel_hi:[0,1,1]
	v_pk_fma_f32 v[32:33], s[22:23], v[52:53], v[32:33] op_sel_hi:[0,1,1]
	v_readlane_b32 s22, v89, 11
	s_waitcnt vmcnt(4)
	v_cvt_scalef32_pk_f32_fp4 v[52:53], v50, 1.0
	v_cvt_scalef32_pk_f32_fp4 v[54:55], v50, 1.0 op_sel:[1,0,0]
	v_cvt_scalef32_pk_f32_fp4 v[56:57], v50, 1.0 op_sel:[0,1,0]
	v_cvt_scalef32_pk_f32_fp4 v[58:59], v50, 1.0 op_sel:[1,1,0]
	v_cvt_scalef32_pk_f32_fp4 v[60:61], v51, 1.0
	v_cvt_scalef32_pk_f32_fp4 v[62:63], v51, 1.0 op_sel:[1,0,0]
	v_cvt_scalef32_pk_f32_fp4 v[64:65], v51, 1.0 op_sel:[0,1,0]
	v_cvt_scalef32_pk_f32_fp4 v[50:51], v51, 1.0 op_sel:[1,1,0]
	v_pk_fma_f32 v[38:39], v[52:53], s[22:23], v[38:39] op_sel_hi:[1,0,1]
	v_pk_fma_f32 v[40:41], s[22:23], v[54:55], v[40:41] op_sel_hi:[0,1,1]
	v_pk_fma_f32 v[34:35], s[22:23], v[56:57], v[34:35] op_sel_hi:[0,1,1]
	v_pk_fma_f32 v[36:37], s[22:23], v[58:59], v[36:37] op_sel_hi:[0,1,1]
	v_pk_fma_f32 v[28:29], s[22:23], v[60:61], v[28:29] op_sel_hi:[0,1,1]
	v_pk_fma_f32 v[30:31], s[22:23], v[62:63], v[30:31] op_sel_hi:[0,1,1]
	v_pk_fma_f32 v[26:27], s[22:23], v[64:65], v[26:27] op_sel_hi:[0,1,1]
	v_pk_fma_f32 v[32:33], s[22:23], v[50:51], v[32:33] op_sel_hi:[0,1,1]
	v_readlane_b32 s22, v89, 12
	s_waitcnt vmcnt(3)
	v_cvt_scalef32_pk_f32_fp4 v[50:51], v48, 1.0
	v_cvt_scalef32_pk_f32_fp4 v[52:53], v48, 1.0 op_sel:[1,0,0]
	v_cvt_scalef32_pk_f32_fp4 v[54:55], v48, 1.0 op_sel:[0,1,0]
	v_cvt_scalef32_pk_f32_fp4 v[56:57], v48, 1.0 op_sel:[1,1,0]
	v_cvt_scalef32_pk_f32_fp4 v[58:59], v49, 1.0
	v_cvt_scalef32_pk_f32_fp4 v[60:61], v49, 1.0 op_sel:[1,0,0]
	v_cvt_scalef32_pk_f32_fp4 v[62:63], v49, 1.0 op_sel:[0,1,0]
	v_cvt_scalef32_pk_f32_fp4 v[48:49], v49, 1.0 op_sel:[1,1,0]
	v_pk_fma_f32 v[38:39], v[50:51], s[22:23], v[38:39] op_sel_hi:[1,0,1]
	v_pk_fma_f32 v[40:41], s[22:23], v[52:53], v[40:41] op_sel_hi:[0,1,1]
	v_pk_fma_f32 v[34:35], s[22:23], v[54:55], v[34:35] op_sel_hi:[0,1,1]
	v_pk_fma_f32 v[36:37], s[22:23], v[56:57], v[36:37] op_sel_hi:[0,1,1]
	v_pk_fma_f32 v[28:29], s[22:23], v[58:59], v[28:29] op_sel_hi:[0,1,1]
	v_pk_fma_f32 v[30:31], s[22:23], v[60:61], v[30:31] op_sel_hi:[0,1,1]
	v_pk_fma_f32 v[26:27], s[22:23], v[62:63], v[26:27] op_sel_hi:[0,1,1]
	v_pk_fma_f32 v[32:33], s[22:23], v[48:49], v[32:33] op_sel_hi:[0,1,1]
	v_readlane_b32 s22, v89, 13
	s_waitcnt vmcnt(2)
	v_cvt_scalef32_pk_f32_fp4 v[48:49], v46, 1.0
	v_cvt_scalef32_pk_f32_fp4 v[50:51], v46, 1.0 op_sel:[1,0,0]
	v_cvt_scalef32_pk_f32_fp4 v[52:53], v46, 1.0 op_sel:[0,1,0]
	v_cvt_scalef32_pk_f32_fp4 v[54:55], v46, 1.0 op_sel:[1,1,0]
	v_cvt_scalef32_pk_f32_fp4 v[56:57], v47, 1.0
	v_cvt_scalef32_pk_f32_fp4 v[58:59], v47, 1.0 op_sel:[1,0,0]
	v_cvt_scalef32_pk_f32_fp4 v[60:61], v47, 1.0 op_sel:[0,1,0]
	v_cvt_scalef32_pk_f32_fp4 v[46:47], v47, 1.0 op_sel:[1,1,0]
	v_pk_fma_f32 v[38:39], v[48:49], s[22:23], v[38:39] op_sel_hi:[1,0,1]
	v_pk_fma_f32 v[40:41], s[22:23], v[50:51], v[40:41] op_sel_hi:[0,1,1]
	v_pk_fma_f32 v[34:35], s[22:23], v[52:53], v[34:35] op_sel_hi:[0,1,1]
	v_pk_fma_f32 v[36:37], s[22:23], v[54:55], v[36:37] op_sel_hi:[0,1,1]
	v_pk_fma_f32 v[28:29], s[22:23], v[56:57], v[28:29] op_sel_hi:[0,1,1]
	v_pk_fma_f32 v[30:31], s[22:23], v[58:59], v[30:31] op_sel_hi:[0,1,1]
	v_pk_fma_f32 v[26:27], s[22:23], v[60:61], v[26:27] op_sel_hi:[0,1,1]
	v_pk_fma_f32 v[32:33], s[22:23], v[46:47], v[32:33] op_sel_hi:[0,1,1]
	v_readlane_b32 s22, v89, 14
	s_waitcnt vmcnt(1)
	v_cvt_scalef32_pk_f32_fp4 v[46:47], v44, 1.0
	v_cvt_scalef32_pk_f32_fp4 v[48:49], v44, 1.0 op_sel:[1,0,0]
	v_cvt_scalef32_pk_f32_fp4 v[50:51], v44, 1.0 op_sel:[0,1,0]
	v_cvt_scalef32_pk_f32_fp4 v[52:53], v44, 1.0 op_sel:[1,1,0]
	v_cvt_scalef32_pk_f32_fp4 v[54:55], v45, 1.0
	v_cvt_scalef32_pk_f32_fp4 v[56:57], v45, 1.0 op_sel:[1,0,0]
	v_cvt_scalef32_pk_f32_fp4 v[58:59], v45, 1.0 op_sel:[0,1,0]
	v_cvt_scalef32_pk_f32_fp4 v[44:45], v45, 1.0 op_sel:[1,1,0]
	v_pk_fma_f32 v[38:39], v[46:47], s[22:23], v[38:39] op_sel_hi:[1,0,1]
	v_pk_fma_f32 v[40:41], s[22:23], v[48:49], v[40:41] op_sel_hi:[0,1,1]
	v_pk_fma_f32 v[34:35], s[22:23], v[50:51], v[34:35] op_sel_hi:[0,1,1]
	v_pk_fma_f32 v[36:37], s[22:23], v[52:53], v[36:37] op_sel_hi:[0,1,1]
	v_pk_fma_f32 v[28:29], s[22:23], v[54:55], v[28:29] op_sel_hi:[0,1,1]
	v_pk_fma_f32 v[30:31], s[22:23], v[56:57], v[30:31] op_sel_hi:[0,1,1]
	v_pk_fma_f32 v[26:27], s[22:23], v[58:59], v[26:27] op_sel_hi:[0,1,1]
	v_pk_fma_f32 v[32:33], s[22:23], v[44:45], v[32:33] op_sel_hi:[0,1,1]
	v_readlane_b32 s38, v89, 15
	s_waitcnt vmcnt(0)
	v_cvt_scalef32_pk_f32_fp4 v[44:45], v42, 1.0
	v_cvt_scalef32_pk_f32_fp4 v[46:47], v42, 1.0 op_sel:[1,0,0]
	v_cvt_scalef32_pk_f32_fp4 v[48:49], v42, 1.0 op_sel:[0,1,0]
	v_cvt_scalef32_pk_f32_fp4 v[50:51], v42, 1.0 op_sel:[1,1,0]
	v_cvt_scalef32_pk_f32_fp4 v[52:53], v43, 1.0
	v_cvt_scalef32_pk_f32_fp4 v[54:55], v43, 1.0 op_sel:[1,0,0]
	v_cvt_scalef32_pk_f32_fp4 v[56:57], v43, 1.0 op_sel:[0,1,0]
	v_cvt_scalef32_pk_f32_fp4 v[42:43], v43, 1.0 op_sel:[1,1,0]
	s_add_i32 s23, s37, -15
	s_add_i32 s22, s37, 1
	v_pk_fma_f32 v[38:39], v[44:45], s[38:39], v[38:39] op_sel_hi:[1,0,1]
	v_pk_fma_f32 v[40:41], s[38:39], v[46:47], v[40:41] op_sel_hi:[0,1,1]
	v_pk_fma_f32 v[34:35], s[38:39], v[48:49], v[34:35] op_sel_hi:[0,1,1]
	v_pk_fma_f32 v[36:37], s[38:39], v[50:51], v[36:37] op_sel_hi:[0,1,1]
	v_pk_fma_f32 v[28:29], s[38:39], v[52:53], v[28:29] op_sel_hi:[0,1,1]
	v_pk_fma_f32 v[30:31], s[38:39], v[54:55], v[30:31] op_sel_hi:[0,1,1]
	v_pk_fma_f32 v[26:27], s[38:39], v[56:57], v[26:27] op_sel_hi:[0,1,1]
	s_cmpk_gt_u32 s23, 0x6f
	v_pk_fma_f32 v[32:33], s[38:39], v[42:43], v[32:33] op_sel_hi:[0,1,1]
	s_cbranch_scc1 .LBB0_1060

.Lg_noepf:
	s_cmp_lt_u32 s22, 64
	s_cselect_b64 vcc, -1, 0
	v_cndmask_b32_e32 v42, v6, v4, vcc
	s_add_i32 s37, s22, 1
	v_readlane_b32 s23, v42, s22
	s_lshl_b32 s23, s23, 9
	v_readlane_b32 s37, v42, s37
	s_lshl_b32 s49, s37, 9
	buffer_load_dwordx2 v[92:93], v72, s[8:11], s49 offen
	s_add_i32 s38, s22, 2
	buffer_load_dwordx2 v[90:91], v72, s[8:11], s23 offen
	v_readlane_b32 s38, v42, s38
	s_lshl_b32 s38, s38, 9
	s_add_i32 s39, s22, 3
	s_add_i32 s40, s22, 4
	s_add_i32 s41, s22, 5
	s_add_i32 s42, s22, 6
	buffer_load_dwordx2 v[94:95], v72, s[8:11], s38 offen
	s_add_i32 s43, s22, 7
	s_add_i32 s44, s22, 8
	s_add_i32 s45, s22, 9
	s_add_i32 s46, s22, 10
	s_add_i32 s47, s22, 11
	s_add_i32 s48, s22, 12
	s_add_i32 s50, s22, 13
	s_add_i32 s51, s22, 14
	s_add_i32 s37, s22, 15
	v_readlane_b32 s39, v42, s39
	v_readlane_b32 s40, v42, s40
	v_readlane_b32 s41, v42, s41
	v_readlane_b32 s42, v42, s42
	v_readlane_b32 s43, v42, s43
	v_readlane_b32 s44, v42, s44
	v_readlane_b32 s45, v42, s45
	v_readlane_b32 s46, v42, s46
	v_readlane_b32 s47, v42, s47
	v_readlane_b32 s48, v42, s48
	v_readlane_b32 s50, v42, s50
	v_readlane_b32 s51, v42, s51
	v_readlane_b32 s52, v42, s37
	s_lshl_b32 s39, s39, 9
	s_lshl_b32 s40, s40, 9
	s_lshl_b32 s41, s41, 9
	s_lshl_b32 s42, s42, 9
	s_lshl_b32 s43, s43, 9
	s_lshl_b32 s44, s44, 9
	s_lshl_b32 s45, s45, 9
	s_lshl_b32 s46, s46, 9
	s_lshl_b32 s47, s47, 9
	s_lshl_b32 s48, s48, 9
	s_lshl_b32 s50, s50, 9
	s_lshl_b32 s51, s51, 9
	s_lshl_b32 s52, s52, 9
	buffer_load_dwordx2 v[96:97], v72, s[8:11], s39 offen
	buffer_load_dwordx2 v[98:99], v72, s[8:11], s40 offen
	buffer_load_dwordx2 v[100:101], v72, s[8:11], s41 offen
	buffer_load_dwordx2 v[102:103], v72, s[8:11], s42 offen
	buffer_load_dwordx2 v[104:105], v72, s[8:11], s43 offen
	buffer_load_dwordx2 v[106:107], v72, s[8:11], s44 offen
	buffer_load_dwordx2 v[108:109], v72, s[8:11], s45 offen
	buffer_load_dwordx2 v[110:111], v72, s[8:11], s46 offen
	buffer_load_dwordx2 v[112:113], v72, s[8:11], s47 offen
	buffer_load_dwordx2 v[114:115], v72, s[8:11], s48 offen
	buffer_load_dwordx2 v[116:117], v72, s[8:11], s50 offen
	buffer_load_dwordx2 v[80:81], v72, s[8:11], s51 offen
	buffer_load_dwordx2 v[78:79], v72, s[8:11], s52 offen
	buffer_load_dwordx2 v[74:75], v72, s[12:15], s23 offen
	buffer_load_dwordx2 v[70:71], v72, s[12:15], s49 offen
	buffer_load_dwordx2 v[68:69], v72, s[12:15], s38 offen
	buffer_load_dwordx2 v[66:67], v72, s[12:15], s39 offen
	buffer_load_dwordx2 v[64:65], v72, s[12:15], s40 offen
	buffer_load_dwordx2 v[62:63], v72, s[12:15], s41 offen
	buffer_load_dwordx2 v[60:61], v72, s[12:15], s42 offen
	buffer_load_dwordx2 v[58:59], v72, s[12:15], s43 offen
	buffer_load_dwordx2 v[56:57], v72, s[12:15], s44 offen
	buffer_load_dwordx2 v[54:55], v72, s[12:15], s45 offen
	buffer_load_dwordx2 v[52:53], v72, s[12:15], s46 offen
	buffer_load_dwordx2 v[50:51], v72, s[12:15], s47 offen
	buffer_load_dwordx2 v[48:49], v72, s[12:15], s48 offen
	buffer_load_dwordx2 v[46:47], v72, s[12:15], s50 offen
	buffer_load_dwordx2 v[44:45], v72, s[12:15], s51 offen
	buffer_load_dwordx2 v[42:43], v72, s[12:15], s52 offen
	s_waitcnt vmcnt(30)
	v_cvt_scalef32_pk_f32_fp4 v[122:123], v90, 1.0 op_sel:[0,1,0]
	v_cvt_scalef32_pk_f32_fp4 v[118:119], v90, 1.0
	v_cvt_scalef32_pk_f32_fp4 v[124:125], v90, 1.0 op_sel:[1,1,0]
	v_pk_mul_f32 v[122:123], v[122:123], v[14:15]
	v_cvt_scalef32_pk_f32_fp4 v[120:121], v90, 1.0 op_sel:[1,0,0]
	v_pk_fma_f32 v[118:119], v[118:119], v[10:11], v[122:123]
	v_pk_mul_f32 v[122:123], v[124:125], v[16:17]
	v_cvt_scalef32_pk_f32_fp4 v[126:127], v91, 1.0
	v_cvt_scalef32_pk_f32_fp4 v[130:131], v91, 1.0 op_sel:[1,0,0]
	v_pk_fma_f32 v[120:121], v[120:121], v[12:13], v[122:123]
	v_cvt_scalef32_pk_f32_fp4 v[134:135], v91, 1.0 op_sel:[0,1,0]
	v_cvt_scalef32_pk_f32_fp4 v[90:91], v91, 1.0 op_sel:[1,1,0]
	v_pk_fma_f32 v[118:119], v[126:127], v[18:19], v[118:119]
	v_pk_fma_f32 v[120:121], v[130:131], v[20:21], v[120:121]
	v_pk_fma_f32 v[118:119], v[134:135], v[22:23], v[118:119]
	v_pk_fma_f32 v[90:91], v[90:91], v[24:25], v[120:121]
	v_cvt_scalef32_pk_f32_fp4 v[120:121], v92, 1.0 op_sel:[0,1,0]
	v_pk_add_f32 v[90:91], v[118:119], v[90:91]
	v_cvt_scalef32_pk_f32_fp4 v[122:123], v92, 1.0 op_sel:[1,1,0]
	v_add_f32_e32 v89, v90, v91
	v_cvt_scalef32_pk_f32_fp4 v[90:91], v92, 1.0
	v_pk_mul_f32 v[120:121], v[120:121], v[14:15]
	v_cvt_scalef32_pk_f32_fp4 v[118:119], v92, 1.0 op_sel:[1,0,0]
	v_pk_fma_f32 v[90:91], v[90:91], v[10:11], v[120:121]
	v_pk_mul_f32 v[120:121], v[122:123], v[16:17]
	v_cvt_scalef32_pk_f32_fp4 v[124:125], v93, 1.0
	v_cvt_scalef32_pk_f32_fp4 v[126:127], v93, 1.0 op_sel:[1,0,0]
	v_pk_fma_f32 v[118:119], v[118:119], v[12:13], v[120:121]
	v_cvt_scalef32_pk_f32_fp4 v[130:131], v93, 1.0 op_sel:[0,1,0]
	v_cvt_scalef32_pk_f32_fp4 v[92:93], v93, 1.0 op_sel:[1,1,0]
	v_pk_fma_f32 v[90:91], v[124:125], v[18:19], v[90:91]
	v_pk_fma_f32 v[118:119], v[126:127], v[20:21], v[118:119]
	v_pk_fma_f32 v[90:91], v[130:131], v[22:23], v[90:91]
	v_pk_fma_f32 v[92:93], v[92:93], v[24:25], v[118:119]
	s_waitcnt vmcnt(29)
	v_cvt_scalef32_pk_f32_fp4 v[118:119], v94, 1.0 op_sel:[0,1,0]
	v_pk_add_f32 v[90:91], v[90:91], v[92:93]
	v_cvt_scalef32_pk_f32_fp4 v[120:121], v94, 1.0 op_sel:[1,1,0]
	v_add_f32_e32 v129, v90, v91
	v_cvt_scalef32_pk_f32_fp4 v[90:91], v94, 1.0
	v_pk_mul_f32 v[118:119], v[118:119], v[14:15]
	v_cvt_scalef32_pk_f32_fp4 v[92:93], v94, 1.0 op_sel:[1,0,0]
	v_pk_fma_f32 v[90:91], v[90:91], v[10:11], v[118:119]
	v_pk_mul_f32 v[118:119], v[120:121], v[16:17]
	v_cvt_scalef32_pk_f32_fp4 v[122:123], v95, 1.0
	v_cvt_scalef32_pk_f32_fp4 v[124:125], v95, 1.0 op_sel:[1,0,0]
	v_pk_fma_f32 v[92:93], v[92:93], v[12:13], v[118:119]
	v_cvt_scalef32_pk_f32_fp4 v[126:127], v95, 1.0 op_sel:[0,1,0]
	v_cvt_scalef32_pk_f32_fp4 v[94:95], v95, 1.0 op_sel:[1,1,0]
	v_pk_fma_f32 v[90:91], v[122:123], v[18:19], v[90:91]
	v_pk_fma_f32 v[92:93], v[124:125], v[20:21], v[92:93]
	v_pk_fma_f32 v[90:91], v[126:127], v[22:23], v[90:91]
	v_pk_fma_f32 v[92:93], v[94:95], v[24:25], v[92:93]
	s_waitcnt vmcnt(28)
	v_cvt_scalef32_pk_f32_fp4 v[94:95], v96, 1.0 op_sel:[0,1,0]
	v_pk_add_f32 v[90:91], v[90:91], v[92:93]
	v_cvt_scalef32_pk_f32_fp4 v[118:119], v96, 1.0 op_sel:[1,1,0]
	v_add_f32_e32 v126, v90, v91
	v_cvt_scalef32_pk_f32_fp4 v[90:91], v96, 1.0
	v_pk_mul_f32 v[94:95], v[94:95], v[14:15]
	v_cvt_scalef32_pk_f32_fp4 v[92:93], v96, 1.0 op_sel:[1,0,0]
	v_pk_fma_f32 v[90:91], v[90:91], v[10:11], v[94:95]
	v_pk_mul_f32 v[94:95], v[118:119], v[16:17]
	v_cvt_scalef32_pk_f32_fp4 v[120:121], v97, 1.0
	v_cvt_scalef32_pk_f32_fp4 v[122:123], v97, 1.0 op_sel:[1,0,0]
	v_pk_fma_f32 v[92:93], v[92:93], v[12:13], v[94:95]
	v_cvt_scalef32_pk_f32_fp4 v[124:125], v97, 1.0 op_sel:[0,1,0]
	v_cvt_scalef32_pk_f32_fp4 v[96:97], v97, 1.0 op_sel:[1,1,0]
	v_pk_fma_f32 v[90:91], v[120:121], v[18:19], v[90:91]
	v_pk_fma_f32 v[92:93], v[122:123], v[20:21], v[92:93]
	v_pk_fma_f32 v[90:91], v[124:125], v[22:23], v[90:91]
	v_pk_fma_f32 v[92:93], v[96:97], v[24:25], v[92:93]
	s_waitcnt vmcnt(27)
	v_cvt_scalef32_pk_f32_fp4 v[94:95], v98, 1.0 op_sel:[0,1,0]
	v_pk_add_f32 v[90:91], v[90:91], v[92:93]
	v_cvt_scalef32_pk_f32_fp4 v[96:97], v98, 1.0 op_sel:[1,1,0]
	v_add_f32_e32 v124, v90, v91
	v_cvt_scalef32_pk_f32_fp4 v[90:91], v98, 1.0
	v_pk_mul_f32 v[94:95], v[94:95], v[14:15]
	v_cvt_scalef32_pk_f32_fp4 v[92:93], v98, 1.0 op_sel:[1,0,0]
	v_pk_fma_f32 v[90:91], v[90:91], v[10:11], v[94:95]
	v_pk_mul_f32 v[94:95], v[96:97], v[16:17]
	v_cvt_scalef32_pk_f32_fp4 v[118:119], v99, 1.0
	v_cvt_scalef32_pk_f32_fp4 v[120:121], v99, 1.0 op_sel:[1,0,0]
	v_pk_fma_f32 v[92:93], v[92:93], v[12:13], v[94:95]
	v_cvt_scalef32_pk_f32_fp4 v[122:123], v99, 1.0 op_sel:[0,1,0]
	v_cvt_scalef32_pk_f32_fp4 v[98:99], v99, 1.0 op_sel:[1,1,0]
	v_pk_fma_f32 v[90:91], v[118:119], v[18:19], v[90:91]
	v_pk_fma_f32 v[92:93], v[120:121], v[20:21], v[92:93]
	v_pk_fma_f32 v[90:91], v[122:123], v[22:23], v[90:91]
	v_pk_fma_f32 v[92:93], v[98:99], v[24:25], v[92:93]
	s_waitcnt vmcnt(26)
	v_cvt_scalef32_pk_f32_fp4 v[94:95], v100, 1.0 op_sel:[0,1,0]
	v_pk_add_f32 v[90:91], v[90:91], v[92:93]
	v_cvt_scalef32_pk_f32_fp4 v[96:97], v100, 1.0 op_sel:[1,1,0]
	v_add_f32_e32 v122, v90, v91
	v_cvt_scalef32_pk_f32_fp4 v[90:91], v100, 1.0
	v_pk_mul_f32 v[94:95], v[94:95], v[14:15]
	v_cvt_scalef32_pk_f32_fp4 v[92:93], v100, 1.0 op_sel:[1,0,0]
	v_pk_fma_f32 v[90:91], v[90:91], v[10:11], v[94:95]
	v_pk_mul_f32 v[94:95], v[96:97], v[16:17]
	v_cvt_scalef32_pk_f32_fp4 v[98:99], v101, 1.0
	v_cvt_scalef32_pk_f32_fp4 v[118:119], v101, 1.0 op_sel:[1,0,0]
	v_pk_fma_f32 v[92:93], v[92:93], v[12:13], v[94:95]
	v_cvt_scalef32_pk_f32_fp4 v[120:121], v101, 1.0 op_sel:[0,1,0]
	v_cvt_scalef32_pk_f32_fp4 v[100:101], v101, 1.0 op_sel:[1,1,0]
	v_pk_fma_f32 v[90:91], v[98:99], v[18:19], v[90:91]
	v_pk_fma_f32 v[92:93], v[118:119], v[20:21], v[92:93]
	v_pk_fma_f32 v[90:91], v[120:121], v[22:23], v[90:91]
	v_pk_fma_f32 v[92:93], v[100:101], v[24:25], v[92:93]
	s_waitcnt vmcnt(25)
	v_cvt_scalef32_pk_f32_fp4 v[94:95], v102, 1.0 op_sel:[0,1,0]
	v_pk_add_f32 v[90:91], v[90:91], v[92:93]
	v_cvt_scalef32_pk_f32_fp4 v[96:97], v102, 1.0 op_sel:[1,1,0]
	v_add_f32_e32 v120, v90, v91
	v_cvt_scalef32_pk_f32_fp4 v[90:91], v102, 1.0
	v_pk_mul_f32 v[94:95], v[94:95], v[14:15]
	v_cvt_scalef32_pk_f32_fp4 v[92:93], v102, 1.0 op_sel:[1,0,0]
	v_pk_fma_f32 v[90:91], v[90:91], v[10:11], v[94:95]
	v_pk_mul_f32 v[94:95], v[96:97], v[16:17]
	v_cvt_scalef32_pk_f32_fp4 v[98:99], v103, 1.0
	v_cvt_scalef32_pk_f32_fp4 v[100:101], v103, 1.0 op_sel:[1,0,0]
	v_pk_fma_f32 v[92:93], v[92:93], v[12:13], v[94:95]
	v_cvt_scalef32_pk_f32_fp4 v[118:119], v103, 1.0 op_sel:[0,1,0]
	v_cvt_scalef32_pk_f32_fp4 v[102:103], v103, 1.0 op_sel:[1,1,0]
	v_pk_fma_f32 v[90:91], v[98:99], v[18:19], v[90:91]
	v_pk_fma_f32 v[92:93], v[100:101], v[20:21], v[92:93]
	v_pk_fma_f32 v[90:91], v[118:119], v[22:23], v[90:91]
	v_pk_fma_f32 v[92:93], v[102:103], v[24:25], v[92:93]
	s_waitcnt vmcnt(24)
	v_cvt_scalef32_pk_f32_fp4 v[94:95], v104, 1.0 op_sel:[0,1,0]
	v_pk_add_f32 v[90:91], v[90:91], v[92:93]
	v_cvt_scalef32_pk_f32_fp4 v[96:97], v104, 1.0 op_sel:[1,1,0]
	v_add_f32_e32 v118, v90, v91
	v_cvt_scalef32_pk_f32_fp4 v[90:91], v104, 1.0
	v_pk_mul_f32 v[94:95], v[94:95], v[14:15]
	v_cvt_scalef32_pk_f32_fp4 v[92:93], v104, 1.0 op_sel:[1,0,0]
	v_pk_fma_f32 v[90:91], v[90:91], v[10:11], v[94:95]
	v_pk_mul_f32 v[94:95], v[96:97], v[16:17]
	v_cvt_scalef32_pk_f32_fp4 v[98:99], v105, 1.0
	v_cvt_scalef32_pk_f32_fp4 v[100:101], v105, 1.0 op_sel:[1,0,0]
	v_pk_fma_f32 v[92:93], v[92:93], v[12:13], v[94:95]
	v_cvt_scalef32_pk_f32_fp4 v[102:103], v105, 1.0 op_sel:[0,1,0]
	v_cvt_scalef32_pk_f32_fp4 v[104:105], v105, 1.0 op_sel:[1,1,0]
	v_pk_fma_f32 v[90:91], v[98:99], v[18:19], v[90:91]
	v_pk_fma_f32 v[92:93], v[100:101], v[20:21], v[92:93]
	v_pk_fma_f32 v[90:91], v[102:103], v[22:23], v[90:91]
	v_pk_fma_f32 v[92:93], v[104:105], v[24:25], v[92:93]
	s_waitcnt vmcnt(23)
	v_cvt_scalef32_pk_f32_fp4 v[94:95], v106, 1.0 op_sel:[0,1,0]
	v_pk_add_f32 v[90:91], v[90:91], v[92:93]
	v_cvt_scalef32_pk_f32_fp4 v[96:97], v106, 1.0 op_sel:[1,1,0]
	v_add_f32_e32 v119, v90, v91
	v_cvt_scalef32_pk_f32_fp4 v[90:91], v106, 1.0
	v_pk_mul_f32 v[94:95], v[94:95], v[14:15]
	v_cvt_scalef32_pk_f32_fp4 v[92:93], v106, 1.0 op_sel:[1,0,0]
	v_pk_fma_f32 v[90:91], v[90:91], v[10:11], v[94:95]
	v_pk_mul_f32 v[94:95], v[96:97], v[16:17]
	v_cvt_scalef32_pk_f32_fp4 v[98:99], v107, 1.0
	v_cvt_scalef32_pk_f32_fp4 v[100:101], v107, 1.0 op_sel:[1,0,0]
	v_pk_fma_f32 v[92:93], v[92:93], v[12:13], v[94:95]
	v_cvt_scalef32_pk_f32_fp4 v[102:103], v107, 1.0 op_sel:[0,1,0]
	v_cvt_scalef32_pk_f32_fp4 v[104:105], v107, 1.0 op_sel:[1,1,0]
	v_pk_fma_f32 v[90:91], v[98:99], v[18:19], v[90:91]
	v_pk_fma_f32 v[92:93], v[100:101], v[20:21], v[92:93]
	v_pk_fma_f32 v[90:91], v[102:103], v[22:23], v[90:91]
	v_pk_fma_f32 v[92:93], v[104:105], v[24:25], v[92:93]
	s_waitcnt vmcnt(22)
	v_cvt_scalef32_pk_f32_fp4 v[94:95], v108, 1.0 op_sel:[0,1,0]
	v_pk_add_f32 v[90:91], v[90:91], v[92:93]
	v_cvt_scalef32_pk_f32_fp4 v[96:97], v108, 1.0 op_sel:[1,1,0]
	v_add_f32_e32 v106, v90, v91
	v_cvt_scalef32_pk_f32_fp4 v[90:91], v108, 1.0
	v_pk_mul_f32 v[94:95], v[94:95], v[14:15]
	v_cvt_scalef32_pk_f32_fp4 v[92:93], v108, 1.0 op_sel:[1,0,0]
	v_pk_fma_f32 v[90:91], v[90:91], v[10:11], v[94:95]
	v_pk_mul_f32 v[94:95], v[96:97], v[16:17]
	v_cvt_scalef32_pk_f32_fp4 v[98:99], v109, 1.0
	v_cvt_scalef32_pk_f32_fp4 v[100:101], v109, 1.0 op_sel:[1,0,0]
	v_pk_fma_f32 v[92:93], v[92:93], v[12:13], v[94:95]
	v_cvt_scalef32_pk_f32_fp4 v[102:103], v109, 1.0 op_sel:[0,1,0]
	v_cvt_scalef32_pk_f32_fp4 v[104:105], v109, 1.0 op_sel:[1,1,0]
	v_pk_fma_f32 v[90:91], v[98:99], v[18:19], v[90:91]
	v_pk_fma_f32 v[92:93], v[100:101], v[20:21], v[92:93]
	v_pk_fma_f32 v[90:91], v[102:103], v[22:23], v[90:91]
	v_pk_fma_f32 v[92:93], v[104:105], v[24:25], v[92:93]
	s_waitcnt vmcnt(21)
	v_cvt_scalef32_pk_f32_fp4 v[94:95], v110, 1.0 op_sel:[0,1,0]
	v_pk_add_f32 v[90:91], v[90:91], v[92:93]
	v_cvt_scalef32_pk_f32_fp4 v[96:97], v110, 1.0 op_sel:[1,1,0]
	v_add_f32_e32 v107, v90, v91
	v_cvt_scalef32_pk_f32_fp4 v[90:91], v110, 1.0
	v_pk_mul_f32 v[94:95], v[94:95], v[14:15]
	v_cvt_scalef32_pk_f32_fp4 v[92:93], v110, 1.0 op_sel:[1,0,0]
	v_pk_fma_f32 v[90:91], v[90:91], v[10:11], v[94:95]
	v_pk_mul_f32 v[94:95], v[96:97], v[16:17]
	v_cvt_scalef32_pk_f32_fp4 v[98:99], v111, 1.0
	v_cvt_scalef32_pk_f32_fp4 v[100:101], v111, 1.0 op_sel:[1,0,0]
	v_pk_fma_f32 v[92:93], v[92:93], v[12:13], v[94:95]
	v_cvt_scalef32_pk_f32_fp4 v[102:103], v111, 1.0 op_sel:[0,1,0]
	v_cvt_scalef32_pk_f32_fp4 v[104:105], v111, 1.0 op_sel:[1,1,0]
	v_pk_fma_f32 v[90:91], v[98:99], v[18:19], v[90:91]
	v_pk_fma_f32 v[92:93], v[100:101], v[20:21], v[92:93]
	v_pk_fma_f32 v[90:91], v[102:103], v[22:23], v[90:91]
	v_pk_fma_f32 v[92:93], v[104:105], v[24:25], v[92:93]
	s_waitcnt vmcnt(20)
	v_cvt_scalef32_pk_f32_fp4 v[94:95], v112, 1.0 op_sel:[0,1,0]
	v_pk_add_f32 v[90:91], v[90:91], v[92:93]
	v_cvt_scalef32_pk_f32_fp4 v[96:97], v112, 1.0 op_sel:[1,1,0]
	v_add_f32_e32 v108, v90, v91
	v_cvt_scalef32_pk_f32_fp4 v[90:91], v112, 1.0
	v_pk_mul_f32 v[94:95], v[94:95], v[14:15]
	v_cvt_scalef32_pk_f32_fp4 v[92:93], v112, 1.0 op_sel:[1,0,0]
	v_pk_fma_f32 v[90:91], v[90:91], v[10:11], v[94:95]
	v_pk_mul_f32 v[94:95], v[96:97], v[16:17]
	v_cvt_scalef32_pk_f32_fp4 v[98:99], v113, 1.0
	v_cvt_scalef32_pk_f32_fp4 v[100:101], v113, 1.0 op_sel:[1,0,0]
	v_pk_fma_f32 v[92:93], v[92:93], v[12:13], v[94:95]
	v_cvt_scalef32_pk_f32_fp4 v[102:103], v113, 1.0 op_sel:[0,1,0]
	v_cvt_scalef32_pk_f32_fp4 v[104:105], v113, 1.0 op_sel:[1,1,0]
	v_pk_fma_f32 v[90:91], v[98:99], v[18:19], v[90:91]
	v_pk_fma_f32 v[92:93], v[100:101], v[20:21], v[92:93]
	v_pk_fma_f32 v[90:91], v[102:103], v[22:23], v[90:91]
	v_pk_fma_f32 v[92:93], v[104:105], v[24:25], v[92:93]
	s_waitcnt vmcnt(19)
	v_cvt_scalef32_pk_f32_fp4 v[94:95], v114, 1.0 op_sel:[0,1,0]
	v_pk_add_f32 v[90:91], v[90:91], v[92:93]
	v_cvt_scalef32_pk_f32_fp4 v[96:97], v114, 1.0 op_sel:[1,1,0]
	v_add_f32_e32 v109, v90, v91
	v_cvt_scalef32_pk_f32_fp4 v[90:91], v114, 1.0
	v_pk_mul_f32 v[94:95], v[94:95], v[14:15]
	v_cvt_scalef32_pk_f32_fp4 v[92:93], v114, 1.0 op_sel:[1,0,0]
	v_pk_fma_f32 v[90:91], v[90:91], v[10:11], v[94:95]
	v_pk_mul_f32 v[94:95], v[96:97], v[16:17]
	v_cvt_scalef32_pk_f32_fp4 v[98:99], v115, 1.0
	v_cvt_scalef32_pk_f32_fp4 v[100:101], v115, 1.0 op_sel:[1,0,0]
	v_pk_fma_f32 v[92:93], v[92:93], v[12:13], v[94:95]
	v_cvt_scalef32_pk_f32_fp4 v[102:103], v115, 1.0 op_sel:[0,1,0]
	v_cvt_scalef32_pk_f32_fp4 v[104:105], v115, 1.0 op_sel:[1,1,0]
	v_pk_fma_f32 v[90:91], v[98:99], v[18:19], v[90:91]
	v_pk_fma_f32 v[92:93], v[100:101], v[20:21], v[92:93]
	v_pk_fma_f32 v[90:91], v[102:103], v[22:23], v[90:91]
	v_pk_fma_f32 v[92:93], v[104:105], v[24:25], v[92:93]
	s_waitcnt vmcnt(18)
	v_cvt_scalef32_pk_f32_fp4 v[94:95], v116, 1.0 op_sel:[0,1,0]
	v_pk_add_f32 v[90:91], v[90:91], v[92:93]
	v_cvt_scalef32_pk_f32_fp4 v[96:97], v116, 1.0 op_sel:[1,1,0]
	v_add_f32_e32 v110, v90, v91
	v_cvt_scalef32_pk_f32_fp4 v[90:91], v116, 1.0
	v_pk_mul_f32 v[94:95], v[94:95], v[14:15]
	v_cvt_scalef32_pk_f32_fp4 v[92:93], v116, 1.0 op_sel:[1,0,0]
	v_pk_fma_f32 v[90:91], v[90:91], v[10:11], v[94:95]
	v_pk_mul_f32 v[94:95], v[96:97], v[16:17]
	v_cvt_scalef32_pk_f32_fp4 v[98:99], v117, 1.0
	v_cvt_scalef32_pk_f32_fp4 v[100:101], v117, 1.0 op_sel:[1,0,0]
	v_pk_fma_f32 v[92:93], v[92:93], v[12:13], v[94:95]
	v_cvt_scalef32_pk_f32_fp4 v[102:103], v117, 1.0 op_sel:[0,1,0]
	v_cvt_scalef32_pk_f32_fp4 v[104:105], v117, 1.0 op_sel:[1,1,0]
	v_pk_fma_f32 v[90:91], v[98:99], v[18:19], v[90:91]
	v_pk_fma_f32 v[92:93], v[100:101], v[20:21], v[92:93]
	v_pk_fma_f32 v[90:91], v[102:103], v[22:23], v[90:91]
	v_pk_fma_f32 v[92:93], v[104:105], v[24:25], v[92:93]
	s_waitcnt vmcnt(17)
	v_cvt_scalef32_pk_f32_fp4 v[94:95], v80, 1.0 op_sel:[0,1,0]
	v_pk_add_f32 v[90:91], v[90:91], v[92:93]
	v_cvt_scalef32_pk_f32_fp4 v[96:97], v80, 1.0 op_sel:[1,1,0]
	v_add_f32_e32 v104, v90, v91
	v_cvt_scalef32_pk_f32_fp4 v[90:91], v80, 1.0
	v_pk_mul_f32 v[94:95], v[94:95], v[14:15]
	v_cvt_scalef32_pk_f32_fp4 v[92:93], v80, 1.0 op_sel:[1,0,0]
	v_pk_fma_f32 v[90:91], v[90:91], v[10:11], v[94:95]
	v_pk_mul_f32 v[94:95], v[96:97], v[16:17]
	v_cvt_scalef32_pk_f32_fp4 v[98:99], v81, 1.0
	v_cvt_scalef32_pk_f32_fp4 v[100:101], v81, 1.0 op_sel:[1,0,0]
	v_pk_fma_f32 v[92:93], v[92:93], v[12:13], v[94:95]
	v_cvt_scalef32_pk_f32_fp4 v[102:103], v81, 1.0 op_sel:[0,1,0]
	v_cvt_scalef32_pk_f32_fp4 v[80:81], v81, 1.0 op_sel:[1,1,0]
	v_pk_fma_f32 v[90:91], v[98:99], v[18:19], v[90:91]
	v_pk_fma_f32 v[92:93], v[100:101], v[20:21], v[92:93]
	v_pk_fma_f32 v[90:91], v[102:103], v[22:23], v[90:91]
	v_pk_fma_f32 v[80:81], v[80:81], v[24:25], v[92:93]
	s_waitcnt vmcnt(16)
	v_cvt_scalef32_pk_f32_fp4 v[92:93], v78, 1.0 op_sel:[0,1,0]
	v_pk_add_f32 v[80:81], v[90:91], v[80:81]
	v_cvt_scalef32_pk_f32_fp4 v[94:95], v78, 1.0 op_sel:[1,1,0]
	v_add_f32_e32 v102, v80, v81
	v_cvt_scalef32_pk_f32_fp4 v[80:81], v78, 1.0
	v_pk_mul_f32 v[92:93], v[92:93], v[14:15]
	v_cvt_scalef32_pk_f32_fp4 v[90:91], v78, 1.0 op_sel:[1,0,0]
	v_pk_fma_f32 v[80:81], v[80:81], v[10:11], v[92:93]
	v_pk_mul_f32 v[92:93], v[94:95], v[16:17]
	v_cvt_scalef32_pk_f32_fp4 v[96:97], v79, 1.0
	v_cvt_scalef32_pk_f32_fp4 v[98:99], v79, 1.0 op_sel:[1,0,0]
	v_pk_fma_f32 v[90:91], v[90:91], v[12:13], v[92:93]
	v_cvt_scalef32_pk_f32_fp4 v[100:101], v79, 1.0 op_sel:[0,1,0]
	v_cvt_scalef32_pk_f32_fp4 v[78:79], v79, 1.0 op_sel:[1,1,0]
	v_pk_fma_f32 v[80:81], v[96:97], v[18:19], v[80:81]
	v_pk_fma_f32 v[90:91], v[98:99], v[20:21], v[90:91]
	v_pk_fma_f32 v[80:81], v[100:101], v[22:23], v[80:81]
	v_pk_fma_f32 v[78:79], v[78:79], v[24:25], v[90:91]
	v_cndmask_b32_e64 v90, v124, v109, s[0:1]
	v_pk_add_f32 v[78:79], v[80:81], v[78:79]
	v_cndmask_b32_e64 v80, v89, v106, s[0:1]
	v_add_f32_e32 v78, v78, v79
	v_cndmask_b32_e64 v79, v106, v89, s[0:1]
	v_cndmask_b32_e64 v81, v129, v107, s[0:1]
	v_cndmask_b32_e64 v89, v126, v108, s[0:1]
	v_add_f32_dpp v79, v80, v79 row_ror:8 row_mask:0xf bank_mask:0xf bound_ctrl:1
	v_cndmask_b32_e64 v80, v107, v129, s[0:1]
	v_cndmask_b32_e64 v91, v122, v110, s[0:1]
	v_cndmask_b32_e64 v92, v120, v104, s[0:1]
	v_add_f32_dpp v80, v81, v80 row_ror:8 row_mask:0xf bank_mask:0xf bound_ctrl:1
	v_cndmask_b32_e64 v81, v108, v126, s[0:1]
	v_cndmask_b32_e64 v93, v118, v102, s[0:1]
	s_nop 0
	v_add_f32_dpp v81, v89, v81 row_ror:8 row_mask:0xf bank_mask:0xf bound_ctrl:1
	v_cndmask_b32_e64 v89, v109, v124, s[0:1]
	s_nop 1
	v_add_f32_dpp v89, v90, v89 row_ror:8 row_mask:0xf bank_mask:0xf bound_ctrl:1
	v_cndmask_b32_e64 v90, v110, v122, s[0:1]
	s_nop 1
	v_add_f32_dpp v90, v91, v90 row_ror:8 row_mask:0xf bank_mask:0xf bound_ctrl:1
	v_cndmask_b32_e64 v91, v104, v120, s[0:1]
	s_nop 1
	v_add_f32_dpp v91, v92, v91 row_ror:8 row_mask:0xf bank_mask:0xf bound_ctrl:1
	v_cndmask_b32_e64 v92, v102, v118, s[0:1]
	s_nop 1
	v_add_f32_dpp v92, v93, v92 row_ror:8 row_mask:0xf bank_mask:0xf bound_ctrl:1
	v_cndmask_b32_e64 v93, v78, v119, s[0:1]
	v_cndmask_b32_e64 v78, v119, v78, s[0:1]
	s_nop 1
	v_add_f32_dpp v78, v78, v93 row_ror:8 row_mask:0xf bank_mask:0xf bound_ctrl:1
	v_cndmask_b32_e64 v93, v90, v79, s[2:3]
	v_cndmask_b32_e64 v79, v79, v90, s[2:3]
	v_cndmask_b32_e64 v90, v91, v80, s[2:3]
	v_cndmask_b32_e64 v80, v80, v91, s[2:3]
	v_add_f32_dpp v79, v79, v93 row_half_mirror row_mask:0xf bank_mask:0xf bound_ctrl:1
	s_nop 0
	v_add_f32_dpp v80, v80, v90 row_half_mirror row_mask:0xf bank_mask:0xf bound_ctrl:1
	v_cndmask_b32_e64 v90, v92, v81, s[2:3]
	v_cndmask_b32_e64 v81, v81, v92, s[2:3]
	s_nop 1
	v_add_f32_dpp v81, v81, v90 row_half_mirror row_mask:0xf bank_mask:0xf bound_ctrl:1
	v_cndmask_b32_e64 v90, v78, v89, s[2:3]
	v_cndmask_b32_e64 v78, v89, v78, s[2:3]
	v_cndmask_b32_e64 v89, v81, v79, s[4:5]
	v_cndmask_b32_e64 v79, v79, v81, s[4:5]
	v_add_f32_dpp v78, v78, v90 row_half_mirror row_mask:0xf bank_mask:0xf bound_ctrl:1
	v_cndmask_b32_e64 v81, v78, v80, s[4:5]
	v_cndmask_b32_e64 v78, v80, v78, s[4:5]
	v_add_f32_dpp v79, v79, v89 quad_perm:[2,3,0,1] row_mask:0xf bank_mask:0xf bound_ctrl:1
	s_nop 0
	v_add_f32_dpp v78, v78, v81 quad_perm:[2,3,0,1] row_mask:0xf bank_mask:0xf bound_ctrl:1
	v_cndmask_b32_e64 v80, v78, v79, s[6:7]
	v_cndmask_b32_e64 v78, v79, v78, s[6:7]
	v_and_or_b32 v81, s22, 48, v83
	v_lshlrev_b32_e32 v81, 2, v81
	v_add_f32_dpp v78, v78, v80 quad_perm:[1,0,3,2] row_mask:0xf bank_mask:0xf bound_ctrl:1
	ds_bpermute_b32 v79, v73, v78
	s_waitcnt lgkmcnt(0)
	v_add_f32_e32 v79, v78, v79
	ds_bpermute_b32 v80, v82, v79
	v_cndmask_b32_e32 v78, v7, v5, vcc
	ds_bpermute_b32 v89, v81, v78
	v_cndmask_b32_e32 v78, v88, v87, vcc
	ds_bpermute_b32 v78, v81, v78
	s_waitcnt lgkmcnt(2)
	v_add_f32_e32 v79, v79, v80
	s_waitcnt lgkmcnt(1)
	v_mul_f32_e32 v79, v79, v89
	v_mul_f32_e32 v80, 0x3f3504f3, v79
	v_cmp_nlt_f32_e64 s[22:23], |v80|, 1.0
	s_and_saveexec_b64 s[38:39], s[22:23]
	s_xor_b64 s[22:23], exec, s[38:39]
	s_cbranch_execz .LBB0_1065
	v_fma_f32 v81, |v80|, s24, v85
	v_fma_f32 v81, |v80|, v81, s25
	v_fma_f32 v81, |v80|, v81, s26
	v_fma_f32 v81, |v80|, v81, s27
	v_fma_f32 v81, |v80|, v81, s28
	v_fma_f32 v81, |v80|, v81, s29
	v_fma_f32 v81, |v80|, v81, |v80|
	v_mul_f32_e32 v89, 0xbfb8aa3b, v81
	v_fma_f32 v90, v81, s30, -v89
	v_rndne_f32_e32 v91, v89
	v_fmac_f32_e32 v90, 0xb2a5705f, v81
	v_sub_f32_e32 v89, v89, v91
	v_add_f32_e32 v89, v89, v90
	v_cvt_i32_f32_e32 v90, v91
	v_exp_f32_e32 v89, v89
	v_cmp_nlt_f32_e32 vcc, s31, v81
	v_ldexp_f32 v89, v89, v90
	s_nop 0
	v_cndmask_b32_e32 v89, 0, v89, vcc
	v_cmp_ngt_f32_e32 vcc, s33, v81
	s_nop 1
	v_cndmask_b32_e32 v81, v86, v89, vcc
	v_sub_f32_e32 v81, 1.0, v81
